# final RMS norm: weight vector loaded once before the row loop instead of four serialized loads per row
# speedup vs baseline: 1.0032x; 1.0002x over previous
; __device__ __forceinline__ int tidx() { int t = threadIdx.x; asm volatile("" : "+v"(t)); return t; }
; __device__ __forceinline__ int bidx() { int b = blockIdx.x; asm volatile("" : "+s"(b)); return b; }
; #define INP(p, i) ldp((p).tbl, i)
; __device__ void phase_final(const Ctx& p) {
;     const int tid = tidx(); const int wave = __builtin_amdgcn_readfirstlane(tid >> 6), lane = tid & 63;
;     const float* nf = INP(p, 29); const float* PART = (const float*)(uptr(p.ws) + OFF_PART);
;     for (int row = bidx() * 8 + wave; row < T_ALL; row += gridDim.x * 8) {
;         float* xp = p.out + (size_t)row * 1024; float4 v[4]; float ss = 0.f;
; #pragma unroll
;         for (int i = 0; i < 4; ++i) { v[i] = *(const float4*)(xp + i * 256 + lane * 4);
;             if (row >= T_P) { const float* pr = PART + (size_t)(row - T_P) * 1024 + i * 256 + lane * 4;
; #pragma unroll
;                 for (int sl = 0; sl < 8; ++sl) { const float4 q = *(const float4*)(pr + (size_t)sl * 1024 * 1024); v[i].x += q.x; v[i].y += q.y; v[i].z += q.z; v[i].w += q.w; } }
;             ss += v[i].x * v[i].x + v[i].y * v[i].y + v[i].z * v[i].z + v[i].w * v[i].w; }
;         const float s = rsqrtf(wsum(ss) * (1.0f / 1024.0f) + 1e-6f);
; #pragma unroll
;         for (int i = 0; i < 4; ++i) { const int c = i * 256 + lane * 4; const float4 w = *(const float4*)(nf + c);
;             v[i].x *= s * w.x; v[i].y *= s * w.y; v[i].z *= s * w.z; v[i].w *= s * w.w; *(float4*)(xp + c) = v[i]; }
;     }
; }
.LBB0_1412:
	v_mov_b64_e32 v[0:1], s[92:93]
	flat_load_dwordx2 v[0:1], v[0:1] offset:232 sc0 sc1
	s_waitcnt vmcnt(0)
	s_mov_b32 s3, s87
	v_readfirstlane_b32 s0, v184
	s_ashr_i32 s0, s0, 6
	s_lshl_b32 s1, s90, 3
	s_add_i32 s2, s1, s0
	s_cmpk_gt_i32 s2, 0x43ff
	s_waitcnt lgkmcnt(0)
	v_readfirstlane_b32 s1, v1
	v_readfirstlane_b32 s0, v0
	s_cbranch_scc1 .LBB0_1423
	v_lshlrev_b32_e32 v0, 4, v184
	s_mov_b32 s87, s3
	v_and_b32_e32 v0, 0x3f0, v0
	v_mov_b32_e32 v1, 0
	v_lshl_add_u64 v[2:3], s[86:87], 0, v[0:1]
	s_mov_b64 s[4:5], 0xdd00000
	v_lshl_add_u64 v[16:17], v[2:3], 0, s[4:5]
	v_and_b32_e32 v2, 64, v189
	v_add_u32_e32 v2, 64, v2
	v_xor_b32_e32 v3, 32, v189
	v_cmp_lt_i32_e32 vcc, v3, v2
	s_mov_b32 s5, 0
	v_lshl_add_u64 v[18:19], s[0:1], 0, v[0:1]
	v_cndmask_b32_e32 v3, v189, v3, vcc
	v_lshlrev_b32_e32 v26, 2, v3
	v_xor_b32_e32 v3, 16, v189
	v_cmp_lt_i32_e32 vcc, v3, v2
	v_lshl_add_u64 v[20:21], s[84:85], 0, v[0:1]
	s_mov_b32 s8, 0x800000
	v_cndmask_b32_e32 v3, v189, v3, vcc
	v_lshlrev_b32_e32 v27, 2, v3
	v_xor_b32_e32 v3, 8, v189
	v_cmp_lt_i32_e32 vcc, v3, v2
	v_mov_b32_e32 v32, 0x358637bd
	s_nop 0
	v_cndmask_b32_e32 v3, v189, v3, vcc
	v_lshlrev_b32_e32 v28, 2, v3
	v_xor_b32_e32 v3, 4, v189
	v_cmp_lt_i32_e32 vcc, v3, v2
	s_nop 1
	v_cndmask_b32_e32 v3, v189, v3, vcc
	v_lshlrev_b32_e32 v29, 2, v3
	v_xor_b32_e32 v3, 2, v189
	v_cmp_lt_i32_e32 vcc, v3, v2
	s_nop 1
	v_cndmask_b32_e32 v3, v189, v3, vcc
	v_lshlrev_b32_e32 v30, 2, v3
	v_xor_b32_e32 v3, 1, v189
	v_cmp_lt_i32_e32 vcc, v3, v2
	s_nop 1
	v_cndmask_b32_e32 v2, v189, v3, vcc
	v_lshlrev_b32_e32 v31, 2, v2
	global_load_dwordx4 v[100:103], v[18:19], off
	global_load_dwordx4 v[104:107], v[18:19], off offset:1024
	global_load_dwordx4 v[108:111], v[18:19], off offset:2048
	global_load_dwordx4 v[112:115], v[18:19], off offset:3072
	s_waitcnt vmcnt(0)
	s_branch .LBB0_1415
.LBB0_1414:
	s_waitcnt vmcnt(3)
	v_pk_mul_f32 v[24:25], v[0:1], v[0:1]
	s_waitcnt vmcnt(2)
	v_pk_mul_f32 v[40:41], v[4:5], v[4:5]
	v_pk_mul_f32 v[38:39], v[2:3], v[2:3]
	v_pk_mul_f32 v[42:43], v[6:7], v[6:7]
	s_waitcnt vmcnt(1)
	v_pk_mul_f32 v[44:45], v[8:9], v[8:9]
	v_add_f32_e32 v33, v41, v40
	v_add_f32_e32 v24, v25, v24
	v_pk_mul_f32 v[46:47], v[10:11], v[10:11]
	s_waitcnt vmcnt(0)
	v_pk_mul_f32 v[48:49], v[12:13], v[12:13]
	v_add_f32_e32 v25, v45, v44
	v_add_f32_e32 v33, v42, v33
	v_add_f32_e32 v24, v38, v24
	v_pk_mul_f32 v[50:51], v[14:15], v[14:15]
	v_add_f32_e32 v40, v49, v48
	v_add_f32_e32 v25, v46, v25
	v_add_f32_e32 v33, v43, v33
	v_add_f32_e32 v24, v39, v24
	v_add_f32_e32 v38, v50, v40
	v_add_f32_e32 v25, v47, v25
	v_add_f32_e32 v24, v24, v33
	v_add_f32_e32 v38, v51, v38
	v_add_f32_e32 v24, v24, v25
	v_add_f32_e32 v24, v24, v38
	ds_bpermute_b32 v25, v26, v24
	s_add_i32 s2, s2, s66
	s_cmpk_lt_i32 s2, 0x4400
	s_waitcnt lgkmcnt(0)
	v_add_f32_e32 v24, v24, v25
	ds_bpermute_b32 v25, v27, v24
	s_waitcnt lgkmcnt(0)
	v_add_f32_e32 v24, v24, v25
	ds_bpermute_b32 v25, v28, v24
	s_waitcnt lgkmcnt(0)
	v_add_f32_e32 v24, v24, v25
	ds_bpermute_b32 v25, v29, v24
	s_waitcnt lgkmcnt(0)
	v_add_f32_e32 v24, v24, v25
	ds_bpermute_b32 v25, v30, v24
	s_waitcnt lgkmcnt(0)
	v_add_f32_e32 v24, v24, v25
	ds_bpermute_b32 v25, v31, v24
	s_waitcnt lgkmcnt(0)
	v_add_f32_e32 v24, v24, v25
	v_fmamk_f32 v24, v24, 0x3a800000, v32
	v_mul_f32_e32 v25, 0x4b800000, v24
	v_cmp_gt_f32_e32 vcc, s8, v24
	s_nop 1
	v_cndmask_b32_e32 v24, v24, v25, vcc
	v_rsq_f32_e32 v24, v24
	s_nop 0
	v_mul_f32_e32 v25, 0x45800000, v24
	v_cndmask_b32_e32 v24, v24, v25, vcc
	v_pk_mul_f32 v[34:35], v[100:101], v[24:25] op_sel_hi:[1,0]
	v_pk_mul_f32 v[36:37], v[102:103], v[24:25] op_sel_hi:[1,0]
	v_pk_mul_f32 v[0:1], v[0:1], v[34:35]
	v_pk_mul_f32 v[2:3], v[2:3], v[36:37]
	global_store_dwordx4 v[22:23], v[0:3], off
	s_nop 1
	v_pk_mul_f32 v[0:1], v[104:105], v[24:25] op_sel_hi:[1,0]
	v_pk_mul_f32 v[2:3], v[106:107], v[24:25] op_sel_hi:[1,0]
	v_pk_mul_f32 v[0:1], v[4:5], v[0:1]
	v_pk_mul_f32 v[2:3], v[6:7], v[2:3]
	global_store_dwordx4 v[22:23], v[0:3], off offset:1024
	s_nop 1
	v_pk_mul_f32 v[0:1], v[24:25], v[108:109] op_sel_hi:[0,1]
	v_pk_mul_f32 v[2:3], v[24:25], v[110:111] op_sel_hi:[0,1]
	v_pk_mul_f32 v[0:1], v[8:9], v[0:1]
	v_pk_mul_f32 v[2:3], v[10:11], v[2:3]
	global_store_dwordx4 v[22:23], v[0:3], off offset:2048
	s_nop 1
	v_pk_mul_f32 v[0:1], v[24:25], v[112:113] op_sel_hi:[0,1]
	v_pk_mul_f32 v[2:3], v[24:25], v[114:115] op_sel_hi:[0,1]
	v_pk_mul_f32 v[0:1], v[12:13], v[0:1]
	v_pk_mul_f32 v[2:3], v[14:15], v[2:3]
	global_store_dwordx4 v[22:23], v[0:3], off offset:3072
	s_cbranch_scc0 .LBB0_1423
